# phase 0: gate biases loaded once before the row loop instead of 8 serial loads per row
# speedup vs baseline: 1.0830x; 1.0012x over previous
; __device__ __forceinline__ void phase0(const Params& P, unsigned char* shm) {
;     ...
;     bf16_t* XB = (bf16_t*)(ws + O_XB); float* gif = (float*)(ws + O_GIF);
;     for (int row = blockIdx.x * 8 + wave; row < MP; row += gridDim.x * 8) {
;         const float* xr = row < ROW_S ? P.in[0] + (size_t)row * D : row < ROW_META ? P.in[1] + (size_t)(row - ROW_S) * D : row < ROW_META + 16 ? P.in[7] + (size_t)(row - ROW_META) * D : nullptr;
;     ...
;             for (int q = 0; q < 8; ++q) gif[(size_t)row * 8 + q] = xr ? s[q] + P.in[9][q] : 0.f; }
.LBB0_25:
	s_or_b64 exec, exec, s[0:1]
	v_lshl_add_u32 v32, s94, 3, v215
	s_movk_i32 s0, 0x2100
	v_cmp_gt_i32_e32 vcc, s0, v32
	s_waitcnt lgkmcnt(0)
	s_barrier
	s_and_saveexec_b64 s[0:1], vcc
	s_cbranch_execz .LBB0_70
	v_and_b32_e32 v1, 63, v214
	s_add_u32 s6, s12, 0x4500000
	v_lshlrev_b32_e32 v0, 2, v1
	v_mov_b32_e32 v35, 0
	v_lshlrev_b32_e32 v34, 3, v1
	s_addc_u32 s7, s13, 0
	v_cmp_eq_u32_e64 s[2:3], 0, v1
	v_lshl_add_u32 v42, v1, 4, 0
	s_lshl_b32 s18, s96, 3
	v_lshl_add_u64 v[36:37], s[12:13], 0, v[34:35]
	s_mov_b64 s[8:9], 0
	v_lshlrev_b32_e32 v38, 2, v0
	v_mov_b32_e32 v39, v35
	v_readlane_b32 s54, v245, 4
	v_readlane_b32 s55, v245, 5
	s_nop 4
	global_load_dword v60, v35, s[54:55]
	global_load_dword v61, v35, s[54:55] offset:4
	global_load_dword v62, v35, s[54:55] offset:8
	global_load_dword v63, v35, s[54:55] offset:12
	global_load_dword v64, v35, s[54:55] offset:16
	global_load_dword v65, v35, s[54:55] offset:20
	global_load_dword v66, v35, s[54:55] offset:24
	global_load_dword v67, v35, s[54:55] offset:28
	s_waitcnt vmcnt(0)
	s_branch .LBB0_29

; __device__ __forceinline__ unsigned cvt_pk_bf16(float lo, float hi) { unsigned r; asm volatile("v_cvt_pk_bf16_f32 %0, %1, %2" : "=v"(r) : "v"(lo), "v"(hi)); return r; }
; __device__ __forceinline__ void phase0(const Params& P, unsigned char* shm) {
;     ...
;         for (int i = 0; i < 8; ++i) { xv[i] = (f32x4){0.f, 0.f, 0.f, 0.f}; if (xr) xv[i] = __builtin_nontemporal_load((const f32x4*)(xr + lane * 4 + 256 * i)); }
; #pragma unroll
;         for (int i = 0; i < 8; ++i) { const int k = lane * 4 + 256 * i; const f32x4 v = xv[i];
;             u32x2 w; w.x = cvt_pk_bf16(v[0], v[1]); w.y = cvt_pk_bf16(v[2], v[3]); *(u32x2*)(XB + (size_t)row * D + k) = w;
; #pragma unroll
;             for (int q = 0; q < 8; ++q) { const f32x4 wv = *(const f32x4*)(wgT + q * 2048 + k); s[q] += v[0] * wv[0] + v[1] * wv[1] + v[2] * wv[2] + v[3] * wv[3]; }
;             asm volatile("" ::: "memory"); }
.LBB0_53:
	s_or_b64 exec, exec, s[10:11]
	s_waitcnt vmcnt(0)
	v_cvt_pk_bf16_f32 v48, v28, v29
	v_cvt_pk_bf16_f32 v49, v30, v31
	ds_read_b128 v[44:47], v42
	v_lshlrev_b64 v[40:41], 12, v[32:33]
	v_lshl_add_u64 v[40:41], v[36:37], 0, v[40:41]
	global_store_dwordx2 v[40:41], v[48:49], off
	ds_read_b128 v[48:51], v42 offset:8192
	s_waitcnt lgkmcnt(1)
	v_mul_f32_e32 v34, v29, v45
	v_fmac_f32_e32 v34, v28, v44
	v_fmac_f32_e32 v34, v30, v46
	v_fmac_f32_e32 v34, v31, v47
	s_waitcnt lgkmcnt(0)
	v_mul_f32_e32 v43, v29, v49
	ds_read_b128 v[44:47], v42 offset:16384
	v_fmac_f32_e32 v43, v28, v48
	v_fmac_f32_e32 v43, v30, v50
	v_fmac_f32_e32 v43, v31, v51
	ds_read_b128 v[48:51], v42 offset:24576
	s_waitcnt lgkmcnt(1)
	v_mul_f32_e32 v45, v29, v45
	v_fmac_f32_e32 v45, v28, v44
	v_fmac_f32_e32 v45, v30, v46
	v_fmac_f32_e32 v45, v31, v47
	s_waitcnt lgkmcnt(0)
	v_mul_f32_e32 v49, v29, v49
	v_add_f32_e32 v52, 0, v45
	v_fmac_f32_e32 v49, v28, v48
	ds_read_b128 v[44:47], v42 offset:32768
	v_fmac_f32_e32 v49, v30, v50
	v_fmac_f32_e32 v49, v31, v51
	v_add_f32_e32 v53, 0, v49
	ds_read_b128 v[48:51], v42 offset:40960
	s_waitcnt lgkmcnt(1)
	v_mul_f32_e32 v45, v29, v45
	v_fmac_f32_e32 v45, v28, v44
	v_fmac_f32_e32 v45, v30, v46
	v_fmac_f32_e32 v45, v31, v47
	s_waitcnt lgkmcnt(0)
	v_mul_f32_e32 v49, v29, v49
	v_add_f32_e32 v54, 0, v45
	v_fmac_f32_e32 v49, v28, v48
	ds_read_b128 v[44:47], v42 offset:49152
	v_fmac_f32_e32 v49, v30, v50
	v_fmac_f32_e32 v49, v31, v51
	v_add_f32_e32 v55, 0, v49
	ds_read_b128 v[48:51], v42 offset:57344
	s_waitcnt lgkmcnt(1)
	v_mul_f32_e32 v45, v29, v45
	v_fmac_f32_e32 v45, v28, v44
	v_fmac_f32_e32 v45, v30, v46
	v_fmac_f32_e32 v45, v31, v47
	s_waitcnt lgkmcnt(0)
	v_mul_f32_e32 v49, v29, v49
	v_add_f32_e32 v56, 0, v45
	v_fmac_f32_e32 v49, v28, v48
	v_cvt_pk_bf16_f32 v28, v24, v25
	v_cvt_pk_bf16_f32 v29, v26, v27
	ds_read_b128 v[44:47], v42 offset:1024
	v_fmac_f32_e32 v49, v30, v50
	v_fmac_f32_e32 v49, v31, v51
	global_store_dwordx2 v[40:41], v[28:29], off offset:512
	ds_read_b128 v[28:31], v42 offset:9216
	s_waitcnt lgkmcnt(1)
	v_mul_f32_e32 v45, v25, v45
	v_fmac_f32_e32 v45, v24, v44
	v_fmac_f32_e32 v45, v26, v46
	v_add_f32_e32 v34, 0, v34
	v_fmac_f32_e32 v45, v27, v47
	s_waitcnt lgkmcnt(0)
	v_mul_f32_e32 v29, v25, v29
	v_add_f32_e32 v34, v34, v45
	v_fmac_f32_e32 v29, v24, v28
	ds_read_b128 v[44:47], v42 offset:17408
	v_fmac_f32_e32 v29, v26, v30
	v_add_f32_e32 v43, 0, v43
	v_fmac_f32_e32 v29, v27, v31
	v_add_f32_e32 v43, v43, v29
	ds_read_b128 v[28:31], v42 offset:25600
	s_waitcnt lgkmcnt(1)
	v_mul_f32_e32 v45, v25, v45
	v_fmac_f32_e32 v45, v24, v44
	v_fmac_f32_e32 v45, v26, v46
	v_fmac_f32_e32 v45, v27, v47
	s_waitcnt lgkmcnt(0)
	v_mul_f32_e32 v29, v25, v29
	v_add_f32_e32 v48, 0, v49
	v_add_f32_e32 v49, v52, v45
	v_fmac_f32_e32 v29, v24, v28
	ds_read_b128 v[44:47], v42 offset:33792
	v_fmac_f32_e32 v29, v26, v30
	v_fmac_f32_e32 v29, v27, v31
	v_add_f32_e32 v50, v53, v29
	ds_read_b128 v[28:31], v42 offset:41984
	s_waitcnt lgkmcnt(1)
	v_mul_f32_e32 v45, v25, v45
	v_fmac_f32_e32 v45, v24, v44
	v_fmac_f32_e32 v45, v26, v46
	v_fmac_f32_e32 v45, v27, v47
	s_waitcnt lgkmcnt(0)
	v_mul_f32_e32 v29, v25, v29
	v_add_f32_e32 v51, v54, v45
	v_fmac_f32_e32 v29, v24, v28
	ds_read_b128 v[44:47], v42 offset:50176
	v_fmac_f32_e32 v29, v26, v30
	v_fmac_f32_e32 v29, v27, v31
	v_add_f32_e32 v52, v55, v29
	ds_read_b128 v[28:31], v42 offset:58368
	s_waitcnt lgkmcnt(1)
	v_mul_f32_e32 v45, v25, v45
	v_fmac_f32_e32 v45, v24, v44
	v_fmac_f32_e32 v45, v26, v46
	v_fmac_f32_e32 v45, v27, v47
	s_waitcnt lgkmcnt(0)
	v_mul_f32_e32 v29, v25, v29
	v_add_f32_e32 v53, v56, v45
	v_fmac_f32_e32 v29, v24, v28
	v_cvt_pk_bf16_f32 v24, v20, v21
	v_cvt_pk_bf16_f32 v25, v22, v23
	ds_read_b128 v[44:47], v42 offset:2048
	v_fmac_f32_e32 v29, v26, v30
	v_fmac_f32_e32 v29, v27, v31
	global_store_dwordx2 v[40:41], v[24:25], off offset:1024
	ds_read_b128 v[24:27], v42 offset:10240
	s_waitcnt lgkmcnt(1)
	v_mul_f32_e32 v28, v21, v45
	v_fmac_f32_e32 v28, v20, v44
	v_fmac_f32_e32 v28, v22, v46
	v_fmac_f32_e32 v28, v23, v47
	s_waitcnt lgkmcnt(0)
	v_mul_f32_e32 v25, v21, v25
	v_add_f32_e32 v48, v48, v29
	v_add_f32_e32 v34, v34, v28
	v_fmac_f32_e32 v25, v20, v24
	ds_read_b128 v[28:31], v42 offset:18432
	v_fmac_f32_e32 v25, v22, v26
	v_fmac_f32_e32 v25, v23, v27
	v_add_f32_e32 v43, v43, v25
	ds_read_b128 v[24:27], v42 offset:26624
	s_waitcnt lgkmcnt(1)
	v_mul_f32_e32 v29, v21, v29
	v_fmac_f32_e32 v29, v20, v28
	v_fmac_f32_e32 v29, v22, v30
	v_fmac_f32_e32 v29, v23, v31
	s_waitcnt lgkmcnt(0)
	v_mul_f32_e32 v25, v21, v25
	v_add_f32_e32 v44, v49, v29
	v_fmac_f32_e32 v25, v20, v24
	ds_read_b128 v[28:31], v42 offset:34816
	v_fmac_f32_e32 v25, v22, v26
	v_fmac_f32_e32 v25, v23, v27
	v_add_f32_e32 v45, v50, v25
	ds_read_b128 v[24:27], v42 offset:43008
	s_waitcnt lgkmcnt(1)
	v_mul_f32_e32 v29, v21, v29
	v_fmac_f32_e32 v29, v20, v28
	v_fmac_f32_e32 v29, v22, v30
	v_fmac_f32_e32 v29, v23, v31
	s_waitcnt lgkmcnt(0)
	v_mul_f32_e32 v25, v21, v25
	v_add_f32_e32 v46, v51, v29
	v_fmac_f32_e32 v25, v20, v24
	ds_read_b128 v[28:31], v42 offset:51200
	v_fmac_f32_e32 v25, v22, v26
	v_fmac_f32_e32 v25, v23, v27
	v_add_f32_e32 v47, v52, v25
	ds_read_b128 v[24:27], v42 offset:59392
	s_waitcnt lgkmcnt(1)
	v_mul_f32_e32 v29, v21, v29
	v_fmac_f32_e32 v29, v20, v28
	v_fmac_f32_e32 v29, v22, v30
	v_fmac_f32_e32 v29, v23, v31
	s_waitcnt lgkmcnt(0)
	v_mul_f32_e32 v25, v21, v25
	v_add_f32_e32 v49, v53, v29
	v_fmac_f32_e32 v25, v20, v24
	v_cvt_pk_bf16_f32 v20, v16, v17
	v_cvt_pk_bf16_f32 v21, v18, v19
	ds_read_b128 v[28:31], v42 offset:3072
	v_fmac_f32_e32 v25, v22, v26
	v_fmac_f32_e32 v25, v23, v27
	global_store_dwordx2 v[40:41], v[20:21], off offset:1536
	ds_read_b128 v[20:23], v42 offset:11264
	s_waitcnt lgkmcnt(1)
; __device__ __forceinline__ unsigned cvt_pk_bf16(float lo, float hi) { unsigned r; asm volatile("v_cvt_pk_bf16_f32 %0, %1, %2" : "=v"(r) : "v"(lo), "v"(hi)); return r; }
; __device__ __forceinline__ void phase0(const Params& P, unsigned char* shm) {
;     ...
;         for (int i = 0; i < 8; ++i) { const int k = lane * 4 + 256 * i; const f32x4 v = xv[i];
;             u32x2 w; w.x = cvt_pk_bf16(v[0], v[1]); w.y = cvt_pk_bf16(v[2], v[3]); *(u32x2*)(XB + (size_t)row * D + k) = w;
; #pragma unroll
;             for (int q = 0; q < 8; ++q) { const f32x4 wv = *(const f32x4*)(wgT + q * 2048 + k); s[q] += v[0] * wv[0] + v[1] * wv[1] + v[2] * wv[2] + v[3] * wv[3]; }
;             asm volatile("" ::: "memory"); }
	v_mul_f32_e32 v24, v17, v29
	v_fmac_f32_e32 v24, v16, v28
	v_fmac_f32_e32 v24, v18, v30
	v_fmac_f32_e32 v24, v19, v31
	s_waitcnt lgkmcnt(0)
	v_mul_f32_e32 v21, v17, v21
	v_add_f32_e32 v48, v48, v25
	v_add_f32_e32 v28, v34, v24
	v_fmac_f32_e32 v21, v16, v20
	ds_read_b128 v[24:27], v42 offset:19456
	v_fmac_f32_e32 v21, v18, v22
	v_fmac_f32_e32 v21, v19, v23
	v_add_f32_e32 v29, v43, v21
	ds_read_b128 v[20:23], v42 offset:27648
	s_waitcnt lgkmcnt(1)
	v_mul_f32_e32 v25, v17, v25
	v_fmac_f32_e32 v25, v16, v24
	v_fmac_f32_e32 v25, v18, v26
	v_fmac_f32_e32 v25, v19, v27
	s_waitcnt lgkmcnt(0)
	v_mul_f32_e32 v21, v17, v21
	v_add_f32_e32 v30, v44, v25
	v_fmac_f32_e32 v21, v16, v20
	ds_read_b128 v[24:27], v42 offset:35840
	v_fmac_f32_e32 v21, v18, v22
	v_fmac_f32_e32 v21, v19, v23
	v_add_f32_e32 v31, v45, v21
	ds_read_b128 v[20:23], v42 offset:44032
	s_waitcnt lgkmcnt(1)
	v_mul_f32_e32 v25, v17, v25
	v_fmac_f32_e32 v25, v16, v24
	v_fmac_f32_e32 v25, v18, v26
	v_fmac_f32_e32 v25, v19, v27
	s_waitcnt lgkmcnt(0)
	v_mul_f32_e32 v21, v17, v21
	v_add_f32_e32 v34, v46, v25
	v_fmac_f32_e32 v21, v16, v20
	ds_read_b128 v[24:27], v42 offset:52224
	v_fmac_f32_e32 v21, v18, v22
	v_fmac_f32_e32 v21, v19, v23
	v_add_f32_e32 v43, v47, v21
	ds_read_b128 v[20:23], v42 offset:60416
	s_waitcnt lgkmcnt(1)
	v_mul_f32_e32 v25, v17, v25
	v_fmac_f32_e32 v25, v16, v24
	v_fmac_f32_e32 v25, v18, v26
	v_fmac_f32_e32 v25, v19, v27
	s_waitcnt lgkmcnt(0)
	v_mul_f32_e32 v21, v17, v21
	v_add_f32_e32 v44, v49, v25
	v_fmac_f32_e32 v21, v16, v20
	v_cvt_pk_bf16_f32 v16, v12, v13
	v_cvt_pk_bf16_f32 v17, v14, v15
	ds_read_b128 v[24:27], v42 offset:4096
	v_fmac_f32_e32 v21, v18, v22
	v_fmac_f32_e32 v21, v19, v23
	global_store_dwordx2 v[40:41], v[16:17], off offset:2048
	ds_read_b128 v[16:19], v42 offset:12288
	s_waitcnt lgkmcnt(1)
	v_mul_f32_e32 v20, v13, v25
	v_fmac_f32_e32 v20, v12, v24
	v_fmac_f32_e32 v20, v14, v26
	v_fmac_f32_e32 v20, v15, v27
	s_waitcnt lgkmcnt(0)
	v_mul_f32_e32 v17, v13, v17
	v_add_f32_e32 v45, v48, v21
	v_add_f32_e32 v24, v28, v20
	v_fmac_f32_e32 v17, v12, v16
	ds_read_b128 v[20:23], v42 offset:20480
	v_fmac_f32_e32 v17, v14, v18
	v_fmac_f32_e32 v17, v15, v19
	v_add_f32_e32 v25, v29, v17
	ds_read_b128 v[16:19], v42 offset:28672
	s_waitcnt lgkmcnt(1)
	v_mul_f32_e32 v21, v13, v21
	v_fmac_f32_e32 v21, v12, v20
	v_fmac_f32_e32 v21, v14, v22
	v_fmac_f32_e32 v21, v15, v23
	s_waitcnt lgkmcnt(0)
	v_mul_f32_e32 v17, v13, v17
	v_add_f32_e32 v26, v30, v21
	v_fmac_f32_e32 v17, v12, v16
	ds_read_b128 v[20:23], v42 offset:36864
	v_fmac_f32_e32 v17, v14, v18
	v_fmac_f32_e32 v17, v15, v19
	v_add_f32_e32 v27, v31, v17
	ds_read_b128 v[16:19], v42 offset:45056
	s_waitcnt lgkmcnt(1)
	v_mul_f32_e32 v21, v13, v21
	v_fmac_f32_e32 v21, v12, v20
	v_fmac_f32_e32 v21, v14, v22
	v_fmac_f32_e32 v21, v15, v23
	s_waitcnt lgkmcnt(0)
	v_mul_f32_e32 v17, v13, v17
	v_add_f32_e32 v28, v34, v21
	v_fmac_f32_e32 v17, v12, v16
	ds_read_b128 v[20:23], v42 offset:53248
	v_fmac_f32_e32 v17, v14, v18
	v_fmac_f32_e32 v17, v15, v19
	v_add_f32_e32 v29, v43, v17
	ds_read_b128 v[16:19], v42 offset:61440
	s_waitcnt lgkmcnt(1)
	v_mul_f32_e32 v21, v13, v21
	v_fmac_f32_e32 v21, v12, v20
	v_fmac_f32_e32 v21, v14, v22
	v_fmac_f32_e32 v21, v15, v23
	s_waitcnt lgkmcnt(0)
	v_mul_f32_e32 v17, v13, v17
	v_add_f32_e32 v30, v44, v21
	v_fmac_f32_e32 v17, v12, v16
	v_cvt_pk_bf16_f32 v12, v8, v9
	v_cvt_pk_bf16_f32 v13, v10, v11
	ds_read_b128 v[20:23], v42 offset:5120
	v_fmac_f32_e32 v17, v14, v18
	v_fmac_f32_e32 v17, v15, v19
	global_store_dwordx2 v[40:41], v[12:13], off offset:2560
	ds_read_b128 v[12:15], v42 offset:13312
	s_waitcnt lgkmcnt(1)
	v_mul_f32_e32 v16, v9, v21
	v_fmac_f32_e32 v16, v8, v20
	v_fmac_f32_e32 v16, v10, v22
	v_fmac_f32_e32 v16, v11, v23
	s_waitcnt lgkmcnt(0)
	v_mul_f32_e32 v13, v9, v13
	v_fmac_f32_e32 v13, v8, v12
	v_add_f32_e32 v31, v45, v17
	v_add_f32_e32 v20, v24, v16
	ds_read_b128 v[16:19], v42 offset:21504
	v_fmac_f32_e32 v13, v10, v14
	v_fmac_f32_e32 v13, v11, v15
	v_add_f32_e32 v21, v25, v13
	ds_read_b128 v[12:15], v42 offset:29696
	s_waitcnt lgkmcnt(1)
	v_mul_f32_e32 v17, v9, v17
	v_fmac_f32_e32 v17, v8, v16
	v_fmac_f32_e32 v17, v10, v18
	v_fmac_f32_e32 v17, v11, v19
	s_waitcnt lgkmcnt(0)
	v_mul_f32_e32 v13, v9, v13
	v_fmac_f32_e32 v13, v8, v12
	v_add_f32_e32 v22, v26, v17
	ds_read_b128 v[16:19], v42 offset:37888
	v_fmac_f32_e32 v13, v10, v14
	v_fmac_f32_e32 v13, v11, v15
	v_add_f32_e32 v23, v27, v13
	ds_read_b128 v[12:15], v42 offset:46080
	s_waitcnt lgkmcnt(1)
	v_mul_f32_e32 v17, v9, v17
	v_fmac_f32_e32 v17, v8, v16
	v_fmac_f32_e32 v17, v10, v18
	v_fmac_f32_e32 v17, v11, v19
	s_waitcnt lgkmcnt(0)
	v_mul_f32_e32 v13, v9, v13
	v_fmac_f32_e32 v13, v8, v12
	v_add_f32_e32 v24, v28, v17
	ds_read_b128 v[16:19], v42 offset:54272
	v_fmac_f32_e32 v13, v10, v14
	v_fmac_f32_e32 v13, v11, v15
	v_add_f32_e32 v25, v29, v13
	ds_read_b128 v[12:15], v42 offset:62464
	s_waitcnt lgkmcnt(1)
	v_mul_f32_e32 v17, v9, v17
	v_fmac_f32_e32 v17, v8, v16
	v_fmac_f32_e32 v17, v10, v18
	v_fmac_f32_e32 v17, v11, v19
	s_waitcnt lgkmcnt(0)
	v_mul_f32_e32 v13, v9, v13
	v_fmac_f32_e32 v13, v8, v12
	v_add_f32_e32 v26, v30, v17
	v_fmac_f32_e32 v13, v10, v14
	v_cvt_pk_bf16_f32 v8, v4, v5
	v_cvt_pk_bf16_f32 v9, v6, v7
	ds_read_b128 v[16:19], v42 offset:6144
	v_fmac_f32_e32 v13, v11, v15
	global_store_dwordx2 v[40:41], v[8:9], off offset:3072
	ds_read_b128 v[8:11], v42 offset:14336
	v_add_f32_e32 v27, v31, v13
	s_waitcnt lgkmcnt(1)
	v_mul_f32_e32 v12, v5, v17
	v_fmac_f32_e32 v12, v4, v16
	v_fmac_f32_e32 v12, v6, v18
	s_waitcnt lgkmcnt(0)
; __device__ __forceinline__ unsigned cvt_pk_bf16(float lo, float hi) { unsigned r; asm volatile("v_cvt_pk_bf16_f32 %0, %1, %2" : "=v"(r) : "v"(lo), "v"(hi)); return r; }
; __device__ __forceinline__ float wave_sum(float v) { v = row16_sum(v); return (lane_bcast(v, 0) + lane_bcast(v, 16)) + (lane_bcast(v, 32) + lane_bcast(v, 48)); }
; __device__ __forceinline__ void phase0(const Params& P, unsigned char* shm) {
;     ...
;         for (int i = 0; i < 8; ++i) { const int k = lane * 4 + 256 * i; const f32x4 v = xv[i];
;             u32x2 w; w.x = cvt_pk_bf16(v[0], v[1]); w.y = cvt_pk_bf16(v[2], v[3]); *(u32x2*)(XB + (size_t)row * D + k) = w;
; #pragma unroll
;             for (int q = 0; q < 8; ++q) { const f32x4 wv = *(const f32x4*)(wgT + q * 2048 + k); s[q] += v[0] * wv[0] + v[1] * wv[1] + v[2] * wv[2] + v[3] * wv[3]; }
;             asm volatile("" ::: "memory"); }
; #pragma unroll
;         for (int q = 0; q < 8; ++q) s[q] = wave_sum(s[q]);
;         if (lane == 0) {
	v_mul_f32_e32 v9, v5, v9
	v_fmac_f32_e32 v9, v4, v8
	v_fmac_f32_e32 v12, v7, v19
	v_fmac_f32_e32 v9, v6, v10
	v_add_f32_e32 v16, v20, v12
	ds_read_b128 v[12:15], v42 offset:22528
	v_fmac_f32_e32 v9, v7, v11
	v_add_f32_e32 v17, v21, v9
	ds_read_b128 v[8:11], v42 offset:30720
	s_waitcnt lgkmcnt(1)
	v_mul_f32_e32 v13, v5, v13
	v_fmac_f32_e32 v13, v4, v12
	v_fmac_f32_e32 v13, v6, v14
	s_waitcnt lgkmcnt(0)
	v_mul_f32_e32 v9, v5, v9
	v_fmac_f32_e32 v9, v4, v8
	v_fmac_f32_e32 v13, v7, v15
	v_fmac_f32_e32 v9, v6, v10
	v_add_f32_e32 v18, v22, v13
	ds_read_b128 v[12:15], v42 offset:38912
	v_fmac_f32_e32 v9, v7, v11
	v_add_f32_e32 v19, v23, v9
	ds_read_b128 v[8:11], v42 offset:47104
	s_waitcnt lgkmcnt(1)
	v_mul_f32_e32 v13, v5, v13
	v_fmac_f32_e32 v13, v4, v12
	v_fmac_f32_e32 v13, v6, v14
	s_waitcnt lgkmcnt(0)
	v_mul_f32_e32 v9, v5, v9
	v_fmac_f32_e32 v9, v4, v8
	v_fmac_f32_e32 v13, v7, v15
	v_fmac_f32_e32 v9, v6, v10
	v_add_f32_e32 v20, v24, v13
	ds_read_b128 v[12:15], v42 offset:55296
	v_fmac_f32_e32 v9, v7, v11
	v_add_f32_e32 v21, v25, v9
	ds_read_b128 v[8:11], v42 offset:63488
	s_waitcnt lgkmcnt(1)
	v_mul_f32_e32 v13, v5, v13
	v_fmac_f32_e32 v13, v4, v12
	v_fmac_f32_e32 v13, v6, v14
	s_waitcnt lgkmcnt(0)
	v_mul_f32_e32 v9, v5, v9
	v_fmac_f32_e32 v9, v4, v8
	v_fmac_f32_e32 v13, v7, v15
	v_fmac_f32_e32 v9, v6, v10
	v_cvt_pk_bf16_f32 v4, v0, v1
	v_cvt_pk_bf16_f32 v5, v2, v3
	v_add_f32_e32 v22, v26, v13
	ds_read_b128 v[12:15], v42 offset:7168
	v_fmac_f32_e32 v9, v7, v11
	global_store_dwordx2 v[40:41], v[4:5], off offset:3584
	ds_read_b128 v[4:7], v42 offset:15360
	v_add_f32_e32 v23, v27, v9
	s_waitcnt lgkmcnt(1)
	v_mul_f32_e32 v8, v1, v13
	v_fmac_f32_e32 v8, v0, v12
	v_fmac_f32_e32 v8, v2, v14
	s_waitcnt lgkmcnt(0)
	v_mul_f32_e32 v5, v1, v5
	v_fmac_f32_e32 v5, v0, v4
	v_fmac_f32_e32 v5, v2, v6
	v_fmac_f32_e32 v8, v3, v15
	v_fmac_f32_e32 v5, v3, v7
	v_add_f32_e32 v12, v16, v8
	ds_read_b128 v[8:11], v42 offset:23552
	v_add_f32_e32 v13, v17, v5
	ds_read_b128 v[4:7], v42 offset:31744
	s_waitcnt lgkmcnt(1)
	v_mul_f32_e32 v9, v1, v9
	v_fmac_f32_e32 v9, v0, v8
	s_waitcnt lgkmcnt(0)
	v_mul_f32_e32 v5, v1, v5
	v_fmac_f32_e32 v5, v0, v4
	v_fmac_f32_e32 v9, v2, v10
	v_fmac_f32_e32 v5, v2, v6
	v_fmac_f32_e32 v9, v3, v11
	v_fmac_f32_e32 v5, v3, v7
	v_add_f32_e32 v14, v18, v9
	ds_read_b128 v[8:11], v42 offset:39936
	v_add_f32_e32 v15, v19, v5
	ds_read_b128 v[4:7], v42 offset:48128
	s_waitcnt lgkmcnt(1)
	v_mul_f32_e32 v9, v1, v9
	v_fmac_f32_e32 v9, v0, v8
	s_waitcnt lgkmcnt(0)
	v_mul_f32_e32 v5, v1, v5
	v_fmac_f32_e32 v5, v0, v4
	v_fmac_f32_e32 v9, v2, v10
	v_fmac_f32_e32 v5, v2, v6
	v_fmac_f32_e32 v9, v3, v11
	v_fmac_f32_e32 v5, v3, v7
	v_add_f32_e32 v16, v20, v9
	ds_read_b128 v[8:11], v42 offset:56320
	v_add_f32_e32 v17, v21, v5
	ds_read_b128 v[4:7], v42 offset:64512
	s_waitcnt lgkmcnt(1)
	v_mul_f32_e32 v9, v1, v9
	v_fmac_f32_e32 v9, v0, v8
	s_waitcnt lgkmcnt(0)
	v_mul_f32_e32 v1, v1, v5
	v_fmac_f32_e32 v1, v0, v4
	v_fmac_f32_e32 v1, v2, v6
	v_fmac_f32_e32 v1, v3, v7
	v_add_f32_e32 v0, v23, v1
	v_fmac_f32_e32 v9, v2, v10
	v_add_f32_dpp v1, v12, v12 row_ror:8 row_mask:0xf bank_mask:0xf bound_ctrl:1
	v_fmac_f32_e32 v9, v3, v11
	v_add_f32_e32 v8, v22, v9
	v_add_f32_dpp v1, v1, v1 row_ror:4 row_mask:0xf bank_mask:0xf bound_ctrl:1
	v_add_f32_dpp v0, v0, v0 row_ror:8 row_mask:0xf bank_mask:0xf bound_ctrl:1
	s_nop 0
	v_add_f32_dpp v1, v1, v1 row_ror:2 row_mask:0xf bank_mask:0xf bound_ctrl:1
	v_add_f32_dpp v0, v0, v0 row_ror:4 row_mask:0xf bank_mask:0xf bound_ctrl:1
	s_nop 0
	v_add_f32_dpp v1, v1, v1 row_ror:1 row_mask:0xf bank_mask:0xf bound_ctrl:1
	v_add_f32_dpp v0, v0, v0 row_ror:2 row_mask:0xf bank_mask:0xf bound_ctrl:1
	v_readlane_b32 s77, v1, 0
	v_readlane_b32 s81, v1, 16
	v_readlane_b32 s78, v1, 32
	v_readlane_b32 s82, v1, 48
	v_add_f32_dpp v1, v13, v13 row_ror:8 row_mask:0xf bank_mask:0xf bound_ctrl:1
	v_add_f32_dpp v0, v0, v0 row_ror:1 row_mask:0xf bank_mask:0xf bound_ctrl:1
	s_nop 0
	v_add_f32_dpp v1, v1, v1 row_ror:4 row_mask:0xf bank_mask:0xf bound_ctrl:1
	v_readlane_b32 s21, v0, 0
	v_readlane_b32 s25, v0, 16
	v_add_f32_dpp v1, v1, v1 row_ror:2 row_mask:0xf bank_mask:0xf bound_ctrl:1
	v_readlane_b32 s22, v0, 32
	v_readlane_b32 s26, v0, 48
	v_add_f32_dpp v1, v1, v1 row_ror:1 row_mask:0xf bank_mask:0xf bound_ctrl:1
	s_nop 0
	v_readlane_b32 s79, v1, 0
	v_readlane_b32 s83, v1, 16
	v_readlane_b32 s80, v1, 32
	v_readlane_b32 s84, v1, 48
	v_add_f32_dpp v1, v14, v14 row_ror:8 row_mask:0xf bank_mask:0xf bound_ctrl:1
	s_nop 1
	v_add_f32_dpp v1, v1, v1 row_ror:4 row_mask:0xf bank_mask:0xf bound_ctrl:1
	s_nop 1
	v_add_f32_dpp v1, v1, v1 row_ror:2 row_mask:0xf bank_mask:0xf bound_ctrl:1
	s_nop 1
	v_add_f32_dpp v1, v1, v1 row_ror:1 row_mask:0xf bank_mask:0xf bound_ctrl:1
	s_nop 0
	v_readlane_b32 s69, v1, 0
	v_readlane_b32 s73, v1, 16
	v_readlane_b32 s70, v1, 32
	v_readlane_b32 s74, v1, 48
	v_add_f32_dpp v1, v15, v15 row_ror:8 row_mask:0xf bank_mask:0xf bound_ctrl:1
	s_nop 1
	v_add_f32_dpp v1, v1, v1 row_ror:4 row_mask:0xf bank_mask:0xf bound_ctrl:1
	s_nop 1
	v_add_f32_dpp v1, v1, v1 row_ror:2 row_mask:0xf bank_mask:0xf bound_ctrl:1
	s_nop 1
	v_add_f32_dpp v1, v1, v1 row_ror:1 row_mask:0xf bank_mask:0xf bound_ctrl:1
	s_nop 0
	v_readlane_b32 s71, v1, 0
	v_readlane_b32 s75, v1, 16
	v_readlane_b32 s72, v1, 32
	v_readlane_b32 s76, v1, 48
	v_add_f32_dpp v1, v16, v16 row_ror:8 row_mask:0xf bank_mask:0xf bound_ctrl:1
	s_nop 1
	v_add_f32_dpp v1, v1, v1 row_ror:4 row_mask:0xf bank_mask:0xf bound_ctrl:1
	s_nop 1
	v_add_f32_dpp v1, v1, v1 row_ror:2 row_mask:0xf bank_mask:0xf bound_ctrl:1
	s_nop 1
	v_add_f32_dpp v1, v1, v1 row_ror:1 row_mask:0xf bank_mask:0xf bound_ctrl:1
	s_nop 0
	v_readlane_b32 s27, v1, 0
	v_readlane_b32 s31, v1, 16
	v_readlane_b32 s28, v1, 32
	v_readlane_b32 s33, v1, 48
	v_add_f32_dpp v1, v17, v17 row_ror:8 row_mask:0xf bank_mask:0xf bound_ctrl:1
	s_nop 1
	v_add_f32_dpp v1, v1, v1 row_ror:4 row_mask:0xf bank_mask:0xf bound_ctrl:1
	s_nop 1
	v_add_f32_dpp v1, v1, v1 row_ror:2 row_mask:0xf bank_mask:0xf bound_ctrl:1
	s_nop 1
	v_add_f32_dpp v1, v1, v1 row_ror:1 row_mask:0xf bank_mask:0xf bound_ctrl:1
	s_nop 0
	v_readlane_b32 s29, v1, 0
	v_readlane_b32 s34, v1, 16
	v_readlane_b32 s30, v1, 32
	v_readlane_b32 s35, v1, 48
	v_add_f32_dpp v1, v8, v8 row_ror:8 row_mask:0xf bank_mask:0xf bound_ctrl:1
	s_nop 1
	v_add_f32_dpp v1, v1, v1 row_ror:4 row_mask:0xf bank_mask:0xf bound_ctrl:1
	s_nop 1
	v_add_f32_dpp v1, v1, v1 row_ror:2 row_mask:0xf bank_mask:0xf bound_ctrl:1
	s_nop 1
	v_add_f32_dpp v1, v1, v1 row_ror:1 row_mask:0xf bank_mask:0xf bound_ctrl:1
	s_nop 0
	v_readlane_b32 s19, v1, 0
	v_readlane_b32 s23, v1, 16
	v_readlane_b32 s20, v1, 32
	v_readlane_b32 s24, v1, 48
	s_and_saveexec_b64 s[10:11], s[2:3]
	s_cbranch_execz .LBB0_28
; __device__ __forceinline__ void phase0(const Params& P, unsigned char* shm) {
;     ...
;         if (lane == 0) {
; #pragma unroll
;             for (int q = 0; q < 8; ++q) gif[(size_t)row * 8 + q] = xr ? s[q] + P.in[9][q] : 0.f; }
	v_lshlrev_b64 v[0:1], 5, v[32:33]
	v_lshl_add_u64 v[0:1], s[6:7], 0, v[0:1]
	s_and_saveexec_b64 s[16:17], s[4:5]
	s_xor_b64 s[16:17], exec, s[16:17]
	s_cbranch_execz .LBB0_56
	v_readlane_b32 s52, v245, 2
	v_readlane_b32 s54, v245, 4
	v_readlane_b32 s55, v245, 5
	v_mov_b32_e32 v3, s81
	v_mov_b32_e32 v4, s82
	v_add_f32_e32 v3, s77, v3
	v_add_f32_e32 v4, s78, v4
	v_add_f32_e32 v3, v3, v4
	v_mov_b32_e32 v2, v60
	v_mov_b32_e32 v4, s84
	v_add_f32_e32 v4, s80, v4
	v_readlane_b32 s53, v245, 3
	v_readlane_b32 s56, v245, 6
	v_readlane_b32 s57, v245, 7
	v_readlane_b32 s58, v245, 8
	v_readlane_b32 s59, v245, 9
	v_readlane_b32 s60, v245, 10
	v_readlane_b32 s61, v245, 11
	v_readlane_b32 s62, v245, 12
	v_readlane_b32 s63, v245, 13
	v_readlane_b32 s64, v245, 14
	v_readlane_b32 s65, v245, 15
	v_readlane_b32 s66, v245, 16
	v_readlane_b32 s67, v245, 17
	s_nop 0
	v_add_f32_e32 v2, v3, v2
	global_store_dword v[0:1], v2, off
	v_mov_b32_e32 v2, v61
	v_mov_b32_e32 v3, s83
	v_add_f32_e32 v3, s79, v3
	v_add_f32_e32 v3, v3, v4
	s_nop 0
	v_add_f32_e32 v2, v3, v2

; __device__ __forceinline__ void phase0(const Params& P, unsigned char* shm) {
;     ...
;         if (lane == 0) {
; #pragma unroll
;             for (int q = 0; q < 8; ++q) gif[(size_t)row * 8 + q] = xr ? s[q] + P.in[9][q] : 0.f; }
.LBB0_58:
	s_or_b64 exec, exec, s[16:17]
	global_store_dword v[0:1], v2, off offset:4
	s_and_saveexec_b64 s[16:17], s[4:5]
	s_xor_b64 s[16:17], exec, s[16:17]
	s_cbranch_execz .LBB0_60
	v_readlane_b32 s52, v245, 2
	v_readlane_b32 s54, v245, 4
	v_readlane_b32 s55, v245, 5
	v_mov_b32_e32 v3, s73
	v_mov_b32_e32 v4, s74
	v_add_f32_e32 v3, s69, v3
	v_add_f32_e32 v4, s70, v4
	v_add_f32_e32 v3, v3, v4
	v_mov_b32_e32 v2, v62
	v_mov_b32_e32 v4, s76
	v_add_f32_e32 v4, s72, v4
	v_readlane_b32 s53, v245, 3
	v_readlane_b32 s56, v245, 6
	v_readlane_b32 s57, v245, 7
	v_readlane_b32 s58, v245, 8
	v_readlane_b32 s59, v245, 9
	v_readlane_b32 s60, v245, 10
	v_readlane_b32 s61, v245, 11
	v_readlane_b32 s62, v245, 12
	v_readlane_b32 s63, v245, 13
	v_readlane_b32 s64, v245, 14
	v_readlane_b32 s65, v245, 15
	v_readlane_b32 s66, v245, 16
	v_readlane_b32 s67, v245, 17
	s_nop 0
	v_add_f32_e32 v2, v3, v2
	global_store_dword v[0:1], v2, off offset:8
	v_mov_b32_e32 v2, v63
	v_mov_b32_e32 v3, s75
	v_add_f32_e32 v3, s71, v3
	v_add_f32_e32 v3, v3, v4
	s_nop 0
	v_add_f32_e32 v2, v3, v2

; __device__ __forceinline__ void phase0(const Params& P, unsigned char* shm) {
;     ...
;         if (lane == 0) {
; #pragma unroll
;             for (int q = 0; q < 8; ++q) gif[(size_t)row * 8 + q] = xr ? s[q] + P.in[9][q] : 0.f; }
.LBB0_62:
	s_or_b64 exec, exec, s[16:17]
	global_store_dword v[0:1], v2, off offset:12
	s_and_saveexec_b64 s[16:17], s[4:5]
	s_xor_b64 s[16:17], exec, s[16:17]
	s_cbranch_execz .LBB0_64
	v_readlane_b32 s52, v245, 2
	v_readlane_b32 s54, v245, 4
	v_readlane_b32 s55, v245, 5
	v_mov_b32_e32 v3, s31
	v_mov_b32_e32 v4, s33
	v_add_f32_e32 v3, s27, v3
	v_add_f32_e32 v4, s28, v4
	v_add_f32_e32 v3, v3, v4
	v_mov_b32_e32 v2, v64
	v_mov_b32_e32 v4, s35
	v_add_f32_e32 v4, s30, v4
	v_readlane_b32 s53, v245, 3
	v_readlane_b32 s56, v245, 6
	v_readlane_b32 s57, v245, 7
	v_readlane_b32 s58, v245, 8
	v_readlane_b32 s59, v245, 9
	v_readlane_b32 s60, v245, 10
	v_readlane_b32 s61, v245, 11
	v_readlane_b32 s62, v245, 12
	v_readlane_b32 s63, v245, 13
	v_readlane_b32 s64, v245, 14
	v_readlane_b32 s65, v245, 15
	v_readlane_b32 s66, v245, 16
	v_readlane_b32 s67, v245, 17
	s_nop 0
	v_add_f32_e32 v2, v3, v2
	global_store_dword v[0:1], v2, off offset:16
	v_mov_b32_e32 v2, v65
	v_mov_b32_e32 v3, s34
	v_add_f32_e32 v3, s29, v3
	v_add_f32_e32 v3, v3, v4
	s_nop 0
	v_add_f32_e32 v2, v3, v2

; __device__ __forceinline__ void phase0(const Params& P, unsigned char* shm) {
;     ...
;         if (lane == 0) {
; #pragma unroll
;             for (int q = 0; q < 8; ++q) gif[(size_t)row * 8 + q] = xr ? s[q] + P.in[9][q] : 0.f; }
.LBB0_66:
	s_or_b64 exec, exec, s[16:17]
	global_store_dword v[0:1], v2, off offset:20
	s_and_saveexec_b64 s[16:17], s[4:5]
	s_xor_b64 s[4:5], exec, s[16:17]
	s_cbranch_execz .LBB0_68
	v_readlane_b32 s52, v245, 2
	v_readlane_b32 s54, v245, 4
	v_readlane_b32 s55, v245, 5
	v_mov_b32_e32 v3, s23
	v_mov_b32_e32 v4, s24
	v_add_f32_e32 v3, s19, v3
	v_add_f32_e32 v4, s20, v4
	v_add_f32_e32 v3, v3, v4
	v_mov_b32_e32 v2, v66
	v_mov_b32_e32 v4, s26
	v_add_f32_e32 v4, s22, v4
	v_readlane_b32 s53, v245, 3
	v_readlane_b32 s56, v245, 6
	v_readlane_b32 s57, v245, 7
	v_readlane_b32 s58, v245, 8
	v_readlane_b32 s59, v245, 9
	v_readlane_b32 s60, v245, 10
	v_readlane_b32 s61, v245, 11
	v_readlane_b32 s62, v245, 12
	v_readlane_b32 s63, v245, 13
	v_readlane_b32 s64, v245, 14
	v_readlane_b32 s65, v245, 15
	v_readlane_b32 s66, v245, 16
	v_readlane_b32 s67, v245, 17
	s_nop 0
	v_add_f32_e32 v2, v3, v2
	global_store_dword v[0:1], v2, off offset:24
	v_mov_b32_e32 v2, v67
	v_mov_b32_e32 v3, s25
	v_add_f32_e32 v3, s21, v3
	v_add_f32_e32 v3, v3, v4
	s_nop 0
	v_add_f32_e32 v2, v3, v2
